# batched LDS read-back also in P0's transposing item body (was 32 serial LDS round trips per item)
# speedup vs baseline: 1.0198x; 1.0082x over previous
; #define LAS __attribute__((address_space(3)))
; #define GAS __attribute__((address_space(1)))
; #define LDS_WAIT() asm volatile("s_waitcnt lgkmcnt(0)" ::: "memory")
; __device__ __forceinline__ void p0_transpose_item(const float* Wsrc  , int ldw, bf16_t* dst  , int ldt, LAS float* scr, int lane) {
;     const int r = lane >> 4, c4 = lane & 15;
;     f32x4 v[16];
; #pragma unroll
;     for (int i = 0; i < 16; ++i) v[i] = __builtin_nontemporal_load((const GAS f32x4*)(Wsrc + (size_t)(4 * i + r) * ldw + 4 * c4));
; #pragma unroll
;     for (int i = 0; i < 16; ++i) { LAS float* s = scr + (4 * i + r) * 65 + 4 * c4; s[0] = v[i].x; s[1] = v[i].y; s[2] = v[i].z; s[3] = v[i].w; }
;     LDS_WAIT(); asm volatile("" ::: "memory");
.LBB0_10:
	v_mul_u32_u24_e32 v2, s54, v10
	v_lshlrev_b32_e32 v2, 2, v2
	v_mul_u32_u24_e32 v66, s54, v11
	v_lshl_add_u64 v[120:121], s[56:57], 0, v[4:5]
	v_lshl_add_u64 v[64:65], v[120:121], 0, v[2:3]
	v_lshlrev_b32_e32 v2, 2, v66
	v_mul_u32_u24_e32 v66, s54, v12
	v_lshl_add_u64 v[68:69], v[120:121], 0, v[2:3]
	v_lshlrev_b32_e32 v2, 2, v66
	v_mul_u32_u24_e32 v66, s54, v13
	v_lshl_add_u64 v[72:73], v[120:121], 0, v[2:3]
	v_lshlrev_b32_e32 v2, 2, v66
	v_mul_u32_u24_e32 v66, s54, v14
	v_lshl_add_u64 v[76:77], v[120:121], 0, v[2:3]
	v_lshlrev_b32_e32 v2, 2, v66
	v_mul_u32_u24_e32 v66, s54, v15
	v_lshl_add_u64 v[80:81], v[120:121], 0, v[2:3]
	v_lshlrev_b32_e32 v2, 2, v66
	v_mul_u32_u24_e32 v66, s54, v16
	v_lshl_add_u64 v[84:85], v[120:121], 0, v[2:3]
	v_lshlrev_b32_e32 v2, 2, v66
	v_mul_u32_u24_e32 v66, s54, v17
	v_lshl_add_u64 v[88:89], v[120:121], 0, v[2:3]
	v_lshlrev_b32_e32 v2, 2, v66
	v_mul_u32_u24_e32 v66, s54, v18
	v_lshl_add_u64 v[92:93], v[120:121], 0, v[2:3]
	v_lshlrev_b32_e32 v2, 2, v66
	v_mul_u32_u24_e32 v66, s54, v19
	v_lshl_add_u64 v[96:97], v[120:121], 0, v[2:3]
	v_lshlrev_b32_e32 v2, 2, v66
	v_mul_u32_u24_e32 v66, s54, v20
	v_lshl_add_u64 v[100:101], v[120:121], 0, v[2:3]
	v_lshlrev_b32_e32 v2, 2, v66
	v_mul_u32_u24_e32 v70, s54, v21
	v_lshl_add_u64 v[104:105], v[120:121], 0, v[2:3]
	v_lshlrev_b32_e32 v2, 2, v70
	v_mul_u32_u24_e32 v82, s54, v22
	v_lshl_add_u64 v[108:109], v[120:121], 0, v[2:3]
	v_lshlrev_b32_e32 v2, 2, v82
	v_mul_u32_u24_e32 v94, s54, v23
	v_lshl_add_u64 v[112:113], v[120:121], 0, v[2:3]
	v_lshlrev_b32_e32 v2, 2, v94
	v_mul_u32_u24_e32 v106, s54, v24
	v_lshl_add_u64 v[116:117], v[120:121], 0, v[2:3]
	v_lshlrev_b32_e32 v2, 2, v106
	v_mul_u32_u24_e32 v118, s54, v25
	v_lshl_add_u64 v[124:125], v[120:121], 0, v[2:3]
	v_lshlrev_b32_e32 v2, 2, v118
	v_lshl_add_u64 v[120:121], v[120:121], 0, v[2:3]
	global_load_dwordx4 v[64:67], v[64:65], off nt
	v_add_u32_e32 v2, 0x3cf0, v35
	global_load_dwordx4 v[68:71], v[68:69], off nt
	v_add_u32_e32 v128, 0x3cf8, v35
	global_load_dwordx4 v[72:75], v[72:73], off nt
	s_add_i32 s69, s69, s28
	global_load_dwordx4 v[76:79], v[76:77], off nt
	s_add_i32 s65, s65, s66
	global_load_dwordx4 v[80:83], v[80:81], off nt
	s_add_i32 s67, s67, s68
	global_load_dwordx4 v[84:87], v[84:85], off nt
	s_cmp_lt_i32 s69, s29
	global_load_dwordx4 v[88:91], v[88:89], off nt
	s_nop 0
	global_load_dwordx4 v[92:95], v[92:93], off nt
	s_nop 0
	global_load_dwordx4 v[96:99], v[96:97], off nt
	s_nop 0
	global_load_dwordx4 v[100:103], v[100:101], off nt
	s_nop 0
	global_load_dwordx4 v[104:107], v[104:105], off nt
	s_nop 0
	global_load_dwordx4 v[108:111], v[108:109], off nt
	s_nop 0
	global_load_dwordx4 v[112:115], v[112:113], off nt
	s_nop 0
	global_load_dwordx4 v[116:119], v[116:117], off nt
	s_nop 0
	global_load_dwordx4 v[120:123], v[120:121], off nt
	s_nop 0
	global_load_dwordx4 v[124:127], v[124:125], off nt
	s_waitcnt vmcnt(15)
	ds_write2_b32 v35, v64, v65 offset1:1
	ds_write2_b32 v35, v66, v67 offset0:2 offset1:3
	s_waitcnt vmcnt(14)
	ds_write2_b32 v36, v68, v69 offset1:1
	ds_write2_b32 v37, v70, v71 offset1:1
	s_waitcnt vmcnt(13)
	ds_write2_b32 v38, v72, v73 offset1:1
	ds_write2_b32 v39, v74, v75 offset1:1
	s_waitcnt vmcnt(12)
	ds_write2_b32 v40, v76, v77 offset1:1
	ds_write2_b32 v41, v78, v79 offset1:1
	s_waitcnt vmcnt(11)
	ds_write2_b32 v42, v80, v81 offset1:1
	ds_write2_b32 v43, v82, v83 offset1:1
	s_waitcnt vmcnt(10)
	ds_write2_b32 v44, v84, v85 offset1:1
	ds_write2_b32 v45, v86, v87 offset1:1
	s_waitcnt vmcnt(9)
	ds_write2_b32 v46, v88, v89 offset1:1
	ds_write2_b32 v47, v90, v91 offset1:1
	s_waitcnt vmcnt(8)
	ds_write2_b32 v48, v92, v93 offset1:1
	ds_write2_b32 v49, v94, v95 offset1:1
	s_waitcnt vmcnt(7)
	ds_write2_b32 v50, v96, v97 offset1:1
	ds_write2_b32 v51, v98, v99 offset1:1
	s_waitcnt vmcnt(6)
	ds_write2_b32 v52, v100, v101 offset1:1
	ds_write2_b32 v53, v102, v103 offset1:1
	s_waitcnt vmcnt(5)
	ds_write2_b32 v54, v104, v105 offset1:1
	ds_write2_b32 v55, v106, v107 offset1:1
	s_waitcnt vmcnt(4)
	ds_write2_b32 v56, v108, v109 offset1:1
	ds_write2_b32 v57, v110, v111 offset1:1
	s_waitcnt vmcnt(3)
	ds_write2_b32 v58, v112, v113 offset1:1
	ds_write2_b32 v59, v114, v115 offset1:1
	s_waitcnt vmcnt(2)
	ds_write2_b32 v60, v116, v117 offset1:1
	ds_write2_b32 v61, v118, v119 offset1:1
	s_waitcnt vmcnt(1)
	ds_write2_b32 v2, v120, v121 offset1:1
	ds_write2_b32 v128, v122, v123 offset1:1
	s_waitcnt vmcnt(0)
; #define LAS __attribute__((address_space(3)))
; #define GAS __attribute__((address_space(1)))
; #define LDS_WAIT() asm volatile("s_waitcnt lgkmcnt(0)" ::: "memory")
; __device__ __forceinline__ unsigned cvt_pk_bf16(float lo, float hi) { unsigned r; asm volatile("v_cvt_pk_bf16_f32 %0, %1, %2" : "=v"(r) : "v"(lo), "v"(hi)); return r; }
; __device__ __forceinline__ void p0_transpose_item(const float* Wsrc  , int ldw, bf16_t* dst  , int ldt, LAS float* scr, int lane) {
;     ...
;     LDS_WAIT(); asm volatile("" ::: "memory");
;     const int c = lane & 7;
; #pragma unroll
;     for (int j = 0; j < 8; ++j) { const int n = (lane >> 3) + 8 * j; const LAS float* s = scr + (8 * c) * 65 + n;
;         u32x4 o; o.x = cvt_pk_bf16(s[0 * 65], s[1 * 65]); o.y = cvt_pk_bf16(s[2 * 65], s[3 * 65]); o.z = cvt_pk_bf16(s[4 * 65], s[5 * 65]); o.w = cvt_pk_bf16(s[6 * 65], s[7 * 65]);
;         *(GAS u32x4*)(dst + (size_t)n * ldt + 8 * c) = o; }
;     LDS_WAIT(); asm volatile("" ::: "memory");
	ds_write2_b32 v62, v124, v125 offset1:1
	ds_write2_b32 v63, v126, v127 offset1:1
	s_waitcnt lgkmcnt(0)
	v_add_u32_e32 v74, 0x400, v27
	ds_read2_b32 v[160:161], v27 offset1:65
	ds_read2_b32 v[162:163], v27 offset0:130 offset1:195
	ds_read2_b32 v[164:165], v74 offset0:4 offset1:69
	ds_read2_b32 v[166:167], v74 offset0:134 offset1:199
	ds_read2_b32 v[168:169], v27 offset0:8 offset1:73
	ds_read2_b32 v[170:171], v27 offset0:138 offset1:203
	ds_read2_b32 v[172:173], v74 offset0:12 offset1:77
	ds_read2_b32 v[174:175], v74 offset0:142 offset1:207
	s_waitcnt lgkmcnt(0)
	v_cvt_pk_bf16_f32 v176, v160, v161
	v_cvt_pk_bf16_f32 v177, v162, v163
	v_cvt_pk_bf16_f32 v178, v164, v165
	v_cvt_pk_bf16_f32 v179, v166, v167
	v_cvt_pk_bf16_f32 v180, v168, v169
	v_cvt_pk_bf16_f32 v181, v170, v171
	v_cvt_pk_bf16_f32 v182, v172, v173
	v_cvt_pk_bf16_f32 v183, v174, v175
	v_mul_u32_u24_e32 v2, s50, v26
	v_lshl_add_u64 v[70:71], s[52:53], 0, v[8:9]
	v_lshlrev_b32_e32 v2, 1, v2
	v_lshl_add_u64 v[72:73], v[70:71], 0, v[2:3]
	global_store_dwordx4 v[72:73], v[176:179], off
	v_mul_u32_u24_e32 v2, s50, v28
	v_lshlrev_b32_e32 v2, 1, v2
	v_lshl_add_u64 v[72:73], v[70:71], 0, v[2:3]
	global_store_dwordx4 v[72:73], v[180:183], off
	ds_read2_b32 v[160:161], v27 offset0:16 offset1:81
	ds_read2_b32 v[162:163], v27 offset0:146 offset1:211
	ds_read2_b32 v[164:165], v74 offset0:20 offset1:85
	ds_read2_b32 v[166:167], v74 offset0:150 offset1:215
	ds_read2_b32 v[168:169], v27 offset0:24 offset1:89
	ds_read2_b32 v[170:171], v27 offset0:154 offset1:219
	ds_read2_b32 v[172:173], v74 offset0:28 offset1:93
	ds_read2_b32 v[174:175], v74 offset0:158 offset1:223
	s_waitcnt lgkmcnt(0)
	v_cvt_pk_bf16_f32 v176, v160, v161
	v_cvt_pk_bf16_f32 v177, v162, v163
	v_cvt_pk_bf16_f32 v178, v164, v165
	v_cvt_pk_bf16_f32 v179, v166, v167
	v_cvt_pk_bf16_f32 v180, v168, v169
	v_cvt_pk_bf16_f32 v181, v170, v171
	v_cvt_pk_bf16_f32 v182, v172, v173
	v_cvt_pk_bf16_f32 v183, v174, v175
	v_mul_u32_u24_e32 v2, s50, v29
	v_lshlrev_b32_e32 v2, 1, v2
	v_lshl_add_u64 v[72:73], v[70:71], 0, v[2:3]
	global_store_dwordx4 v[72:73], v[176:179], off
	v_mul_u32_u24_e32 v2, s50, v30
	v_lshlrev_b32_e32 v2, 1, v2
	v_lshl_add_u64 v[72:73], v[70:71], 0, v[2:3]
	global_store_dwordx4 v[72:73], v[180:183], off
	ds_read2_b32 v[160:161], v27 offset0:32 offset1:97
	ds_read2_b32 v[162:163], v27 offset0:162 offset1:227
	ds_read2_b32 v[164:165], v74 offset0:36 offset1:101
	ds_read2_b32 v[166:167], v74 offset0:166 offset1:231
	ds_read2_b32 v[168:169], v27 offset0:40 offset1:105
	ds_read2_b32 v[170:171], v27 offset0:170 offset1:235
	ds_read2_b32 v[172:173], v74 offset0:44 offset1:109
	ds_read2_b32 v[174:175], v74 offset0:174 offset1:239
	s_waitcnt lgkmcnt(0)
	v_cvt_pk_bf16_f32 v176, v160, v161
	v_cvt_pk_bf16_f32 v177, v162, v163
	v_cvt_pk_bf16_f32 v178, v164, v165
	v_cvt_pk_bf16_f32 v179, v166, v167
	v_cvt_pk_bf16_f32 v180, v168, v169
	v_cvt_pk_bf16_f32 v181, v170, v171
	v_cvt_pk_bf16_f32 v182, v172, v173
	v_cvt_pk_bf16_f32 v183, v174, v175
	v_mul_u32_u24_e32 v2, s50, v31
	v_lshlrev_b32_e32 v2, 1, v2
	v_lshl_add_u64 v[72:73], v[70:71], 0, v[2:3]
	global_store_dwordx4 v[72:73], v[176:179], off
	v_mul_u32_u24_e32 v2, s50, v32
	v_lshlrev_b32_e32 v2, 1, v2
	v_lshl_add_u64 v[72:73], v[70:71], 0, v[2:3]
	global_store_dwordx4 v[72:73], v[180:183], off
	ds_read2_b32 v[160:161], v27 offset0:48 offset1:113
	ds_read2_b32 v[162:163], v27 offset0:178 offset1:243
	ds_read2_b32 v[164:165], v74 offset0:52 offset1:117
	ds_read2_b32 v[166:167], v74 offset0:182 offset1:247
	ds_read2_b32 v[168:169], v27 offset0:56 offset1:121
	ds_read2_b32 v[170:171], v27 offset0:186 offset1:251
	ds_read2_b32 v[172:173], v74 offset0:60 offset1:125
	ds_read2_b32 v[174:175], v74 offset0:190 offset1:255
	s_waitcnt lgkmcnt(0)
	v_cvt_pk_bf16_f32 v176, v160, v161
	v_cvt_pk_bf16_f32 v177, v162, v163
	v_cvt_pk_bf16_f32 v178, v164, v165
	v_cvt_pk_bf16_f32 v179, v166, v167
	v_cvt_pk_bf16_f32 v180, v168, v169
	v_cvt_pk_bf16_f32 v181, v170, v171
	v_cvt_pk_bf16_f32 v182, v172, v173
	v_cvt_pk_bf16_f32 v183, v174, v175
	v_mul_u32_u24_e32 v2, s50, v33
	v_lshlrev_b32_e32 v2, 1, v2
	v_lshl_add_u64 v[72:73], v[70:71], 0, v[2:3]
	v_mul_u32_u24_e32 v2, s50, v34
	global_store_dwordx4 v[72:73], v[176:179], off
	v_lshlrev_b32_e32 v2, 1, v2
	v_lshl_add_u64 v[70:71], v[70:71], 0, v[2:3]
	global_store_dwordx4 v[70:71], v[180:183], off
	s_cbranch_scc0 .LBB0_35
